# diff-attn loop: K tile staged HBM->LDS directly (global_load_lds_dwordx4, XOR swizzle applied on the source address) instead of VGPR + ds_write
# speedup vs baseline: 1.0053x; 1.0053x over previous
; #define SBAR() __builtin_amdgcn_sched_barrier(0)
; #define VMW() asm volatile("s_waitcnt vmcnt(0)" ::: "memory")
; #define SLOAD_H(Kp, Vp, k0) do { S.st_v0 = load8<TIn>(ROW(Vp, k0, sr)); S.st_v1 = load8<TIn>(ROW(Vp, k0, 32 + sr));              \
;                          S.st_k0 = load8<TIn>(ROW(Kp, k0, sr)); S.st_k1 = load8<TIn>(ROW(Kp, k0, 32 + sr)); } while (0)
; #define SWRITE_HV(bf) do { *(bf16x8*)(V_lds + (bf) * SHM_V + vst0) = S.st_v0; *(bf16x8*)(V_lds + (bf) * SHM_V + vst1) = S.st_v1; } while (0)
; #define SWRITE_H(bf) do { SWRITE_HV(bf); SWRITE_HK(bf); } while (0)
; #define ACT(t) (KBASE(t) <= qlo + QBLK - 1 && KBASE(t) + KVBLK - 1 >= qlo - W + 1)
; __device__ __forceinline__ void partialSM(f32x16& p0, f32x16& p1, float& m_reg, float& mn, float& alpha) {
;     float pmax = p0[0]; for (int r = 1; r < 16; ++r) pmax = fmaxf(pmax, p0[r]); for (int r = 0; r < 16; ++r) pmax = fmaxf(pmax, p1[r]);
;     { auto rr = __builtin_amdgcn_permlane32_swap(__float_as_uint(pmax), __float_as_uint(pmax), false, false);
;       pmax = fmaxf(__uint_as_float(rr[0]), __uint_as_float(rr[1])); }
;     constexpr float C2 = 1.4426950408889634f * SCALE;
;     if (__builtin_expect(__all((pmax - m_reg) * SCALE <= THR), 1)) { mn = m_reg; alpha = 1.f; }
;     else { mn = fmaxf(m_reg, pmax); alpha = __builtin_amdgcn_exp2f((m_reg - mn) * C2); m_reg = mn; }
;     const float mnL = -mn * C2;
;     for (int r = 0; r < 16; ++r) p0[r] = fmaf(p0[r], C2, mnL); for (int r = 0; r < 16; ++r) p1[r] = fmaf(p1[r], C2, mnL);
;     for (int r = 0; r < 16; ++r) p0[r] = __builtin_amdgcn_exp2f(p0[r]);
; template <class TIn, class TOut>
; __device__ __forceinline__ void causal_swa_block(const BlockRef<TIn, TOut>& cur, const BlockRef<TIn, TOut>& nxt, int skv, int W, char* lds, Seam<TIn>& S) {
;     ...
;     if constexpr (F32) { VMW(); SWRITE_VF(0); SBAR(); } else { SWRITE_HV(0); SBAR(); }
;     if (NT > 1) { if constexpr (F32) SLOAD_F((const float*)Kh, KBASE(1)); else SLOAD_H(Kh, Vh, KBASE(1)); }
;     SBAR(); qkt<0, SK>(pA0, pA1, K_lds, r32, hi, S.qr, ACT(0));
;     if constexpr (F32) { if (NT > 1) { VMW(); SWRITE_KF(1); SBAR(); SLOAD_F((const float*)Vh, KBASE(1)); } }
;     MASKT(pA0, pA1, 0); partialSM(pA0, pA1, m_reg, mnA, alA);
;     if (NT > 1) { VMW(); if constexpr (F32) { SWRITE_VF(1); SBAR(); if (NT > 2) SLOAD_F((const float*)Kh, KBASE(2)); } else SWRITE_H(1); }
;     __syncthreads();
.LBB0_1128:
	s_nop 8
	v_max_f32_e32 v50, v19, v19
	v_max_f32_e32 v51, v18, v18
	v_max_f32_e32 v50, v51, v50
	v_max3_f32 v50, v50, v20, v21
	v_max3_f32 v50, v50, v22, v23
	v_max3_f32 v50, v50, v24, v25
	v_max3_f32 v50, v50, v26, v27
	v_max3_f32 v50, v50, v28, v29
	v_max3_f32 v50, v50, v30, v31
	v_max3_f32 v50, v50, v32, v33
	v_max3_f32 v50, v50, v2, v3
	v_max3_f32 v50, v50, v4, v5
	v_max3_f32 v50, v50, v6, v7
	v_max3_f32 v50, v50, v8, v9
	v_max3_f32 v50, v50, v10, v11
	v_max3_f32 v50, v50, v12, v13
	v_max3_f32 v50, v50, v14, v15
	v_max3_f32 v50, v50, v16, v17
	v_mov_b32_e32 v51, v50
	s_nop 1
	v_permlane32_swap_b32_e32 v50, v51
	v_max_f32_e32 v51, v51, v51
	v_max_f32_e32 v50, v50, v50
	v_max_f32_e32 v50, v50, v51
	s_and_b32 s4, s4, 0x3fffffc0
	v_add_f32_e32 v51, 0x7149f2ca, v50
	s_lshl_b32 s4, s4, 2
	v_mul_f32_e32 v51, 0x3db504f3, v51
	v_max_f32_e32 v50, 0xf149f2ca, v50
	s_add_i32 s14, s80, 0xff
	s_add_i32 s4, s4, 0
	v_cmp_ge_f32_e32 vcc, s86, v51
	v_sub_f32_e32 v51, 0xf149f2ca, v50
	s_lshr_b32 s24, s14, 6
	s_add_i32 s4, s4, 0x10000
	s_add_i32 s15, s13, 0xffffc01f
	v_mul_f32_e32 v51, 0x3e0293ee, v51
	v_exp_f32_e32 v51, v51
	s_cmp_eq_u64 vcc, exec
	s_cselect_b64 vcc, -1, 0
	v_cndmask_b32_e32 v178, v50, v216, vcc
	v_mul_f32_e32 v50, 0xbe0293ee, v178
	v_cndmask_b32_e64 v197, v51, 1.0, vcc
	v_mov_b32_e32 v51, v50
	v_fmamk_f32 v18, v18, 0x3e0293ee, v50
	v_fmamk_f32 v19, v19, 0x3e0293ee, v50
	v_fmamk_f32 v20, v20, 0x3e0293ee, v50
	v_fmamk_f32 v21, v21, 0x3e0293ee, v50
	v_fmamk_f32 v22, v22, 0x3e0293ee, v50
	v_fmamk_f32 v23, v23, 0x3e0293ee, v50
	v_fmamk_f32 v24, v24, 0x3e0293ee, v50
	v_fmamk_f32 v25, v25, 0x3e0293ee, v50
	v_fmamk_f32 v26, v26, 0x3e0293ee, v50
	v_fmamk_f32 v27, v27, 0x3e0293ee, v50
	v_fmamk_f32 v28, v28, 0x3e0293ee, v50
	v_fmamk_f32 v29, v29, 0x3e0293ee, v50
	v_fmamk_f32 v30, v30, 0x3e0293ee, v50
	v_fmamk_f32 v31, v31, 0x3e0293ee, v50
	v_fmamk_f32 v32, v32, 0x3e0293ee, v50
	v_fmac_f32_e32 v51, 0x3e0293ee, v33
	v_exp_f32_e32 v170, v18
	v_exp_f32_e32 v171, v19
	v_exp_f32_e32 v172, v20
	v_exp_f32_e32 v173, v21
	v_exp_f32_e32 v174, v22
	v_exp_f32_e32 v176, v23
	v_exp_f32_e32 v175, v24
	v_exp_f32_e32 v177, v25
	v_exp_f32_e32 v162, v26
	v_exp_f32_e32 v163, v27
	v_exp_f32_e32 v164, v28
	v_exp_f32_e32 v166, v29
	v_exp_f32_e32 v165, v30
	v_exp_f32_e32 v167, v31
	v_exp_f32_e32 v168, v32
	v_exp_f32_e32 v169, v51
	s_waitcnt vmcnt(0)
	s_waitcnt vmcnt(3)
	ds_write_b128 v209, v[34:37] offset:16384
	s_waitcnt vmcnt(1)
	ds_write_b128 v210, v[46:49] offset:16384
	ds_write_b128 v217, v[38:41] offset:49152
	s_waitcnt vmcnt(0)
	ds_write_b128 v217, v[42:45] offset:57344
	v_mov_b32_e32 v34, v195
	v_mov_b32_e32 v35, v195
	v_mov_b32_e32 v48, v195
	v_mov_b32_e32 v49, v195
	v_pk_fma_f32 v[118:119], v[16:17], s[50:51], v[50:51] op_sel_hi:[1,0,0]
	v_pk_fma_f32 v[122:123], v[14:15], s[50:51], v[50:51] op_sel_hi:[1,0,0]
	v_pk_fma_f32 v[128:129], v[12:13], s[50:51], v[50:51] op_sel_hi:[1,0,0]
	v_pk_fma_f32 v[114:115], v[10:11], s[50:51], v[50:51] op_sel_hi:[1,0,0]
	v_pk_fma_f32 v[116:117], v[8:9], s[50:51], v[50:51] op_sel_hi:[1,0,0]
	v_pk_fma_f32 v[120:121], v[6:7], s[50:51], v[50:51] op_sel_hi:[1,0,0]
	v_pk_fma_f32 v[124:125], v[4:5], s[50:51], v[50:51] op_sel_hi:[1,0,0]
	v_pk_fma_f32 v[126:127], v[2:3], s[50:51], v[50:51] op_sel_hi:[1,0,0]
	v_mov_b32_e32 v36, v195
	v_mov_b32_e32 v37, v195
	v_mov_b32_e32 v38, v195
	v_mov_b32_e32 v39, v195
	v_mov_b32_e32 v40, v195
	v_mov_b32_e32 v41, v195
	v_mov_b32_e32 v42, v195
	v_mov_b32_e32 v43, v195
	v_mov_b32_e32 v44, v195
	v_mov_b32_e32 v45, v195
	v_mov_b32_e32 v46, v195
	v_mov_b32_e32 v47, v195
	v_mov_b64_e32 v[64:65], v[48:49]
	v_mov_b64_e32 v[18:19], v[34:35]
	v_mov_b64_e32 v[2:3], v[34:35]
	s_mov_b32 s25, 2
	v_lshl_add_u32 v219, v199, 2, s4
	v_lshl_add_u32 v218, v200, 2, s4
	v_add_u32_e32 v222, s12, v201
	v_mov_b32_e32 v221, 0
	s_movk_i32 s26, 0xbf
	v_mov_b32_e32 v194, v203
	v_mov_b64_e32 v[62:63], v[46:47]
	v_mov_b64_e32 v[60:61], v[44:45]
	v_mov_b64_e32 v[58:59], v[42:43]
	v_mov_b64_e32 v[56:57], v[40:41]
	v_mov_b64_e32 v[54:55], v[38:39]
	v_mov_b64_e32 v[52:53], v[36:37]
	v_mov_b64_e32 v[50:51], v[34:35]
	v_mov_b64_e32 v[20:21], v[36:37]
	v_mov_b64_e32 v[22:23], v[38:39]
	v_mov_b64_e32 v[24:25], v[40:41]
	v_mov_b64_e32 v[26:27], v[42:43]
	v_mov_b64_e32 v[28:29], v[44:45]
	v_mov_b64_e32 v[30:31], v[46:47]
	v_mov_b64_e32 v[32:33], v[48:49]
	v_mov_b64_e32 v[4:5], v[36:37]
	v_mov_b64_e32 v[6:7], v[38:39]
	v_mov_b64_e32 v[8:9], v[40:41]
	v_mov_b64_e32 v[10:11], v[42:43]
	v_mov_b64_e32 v[12:13], v[44:45]
	v_mov_b64_e32 v[14:15], v[46:47]
	v_mov_b64_e32 v[16:17], v[48:49]
	s_waitcnt lgkmcnt(0)
	s_barrier
	v_lshlrev_b32_e32 v255, 1, v194
	v_mov_b32_e32 v252, v178
	v_mul_f32_e32 v253, 0xbe0293ee, v178
	v_and_b32_e32 v251, 0x70, v1
	v_xor_b32_e32 v251, v251, v255
	v_readfirstlane_b32 s52, v1
	s_nop 3
	s_and_b32 s52, s52, 0x3ff
	s_cmpk_ge_u32 s52, 0x100
	s_cbranch_scc0 .Lattn_prio_skip
	s_setprio 1
.Lattn_prio_skip:
.LBB0_1129:
	ds_read_b128 v[180:183], v211 offset:49152
	ds_read_b128 v[184:187], v211 offset:57344
	ds_read_b128 v[188:191], v212 offset:49152
	ds_read_b128 v[228:231], v212 offset:57344
	ds_read_b128 v[232:235], v213 offset:49152
	ds_read_b128 v[236:239], v213 offset:57344
	ds_read_b128 v[240:243], v214 offset:49152
	ds_read_b128 v[244:247], v214 offset:57344
	v_exp_f32_e32 v126, v126
	v_exp_f32_e32 v127, v127
	v_exp_f32_e32 v124, v124
	v_exp_f32_e32 v125, v125
	v_exp_f32_e32 v120, v120
	v_exp_f32_e32 v121, v121
	s_add_i32 s4, s26, 0xffffff81
	s_sub_i32 s5, s26, 64
	s_waitcnt lgkmcnt(7)
	v_mfma_f32_32x32x16_bf16 v[86:101], v[180:183], v[158:161], 0
	ds_read_b128 v[180:183], v211 offset:49280
	v_exp_f32_e32 v116, v116
	v_exp_f32_e32 v117, v117
	v_exp_f32_e32 v114, v114
	v_exp_f32_e32 v115, v115
	v_exp_f32_e32 v128, v128
	s_waitcnt lgkmcnt(7)
	v_mfma_f32_32x32x16_bf16 v[70:85], v[184:187], v[158:161], 0
	ds_read_b128 v[184:187], v211 offset:57472
	v_exp_f32_e32 v129, v129
	v_exp_f32_e32 v122, v122
	v_exp_f32_e32 v123, v123
	v_exp_f32_e32 v118, v118
	v_exp_f32_e32 v119, v119
	s_waitcnt lgkmcnt(7)
	v_mfma_f32_32x32x16_bf16 v[86:101], v[188:191], v[154:157], v[86:101]
	ds_read_b128 v[188:191], v212 offset:49280
	v_add_f32_e32 v179, 0, v170
	v_add_f32_e32 v179, v171, v179
	v_add_f32_e32 v179, v172, v179
	v_add_f32_e32 v179, v173, v179
	v_add_f32_e32 v179, v174, v179
	s_waitcnt lgkmcnt(7)
	v_mfma_f32_32x32x16_bf16 v[70:85], v[228:231], v[154:157], v[70:85]
	ds_read_b128 v[228:231], v212 offset:57472
	v_add_f32_e32 v179, v176, v179
	v_add_f32_e32 v179, v175, v179
	v_add_f32_e32 v179, v177, v179
	v_add_f32_e32 v179, v162, v179
	v_add_f32_e32 v179, v163, v179
	s_waitcnt lgkmcnt(7)
	v_mfma_f32_32x32x16_bf16 v[86:101], v[232:235], v[150:153], v[86:101]
	ds_read_b128 v[232:235], v213 offset:49280
	v_add_f32_e32 v110, v164, v179
	v_add_f32_e32 v110, v166, v110
	v_add_f32_e32 v110, v165, v110
	v_add_f32_e32 v110, v167, v110
	s_waitcnt lgkmcnt(7)
	v_mfma_f32_32x32x16_bf16 v[70:85], v[236:239], v[150:153], v[70:85]
	ds_read_b128 v[236:239], v213 offset:57472
	v_add_f32_e32 v110, v168, v110
	v_add_f32_e32 v110, v169, v110
	v_add_f32_e32 v110, v126, v110
	v_add_f32_e32 v102, v127, v110
	s_waitcnt lgkmcnt(7)
	v_mfma_f32_32x32x16_bf16 v[86:101], v[240:243], v[134:137], v[86:101]
	ds_read_b128 v[240:243], v214 offset:49280
	v_add_f32_e32 v102, v124, v102
	v_add_f32_e32 v102, v125, v102
	v_add_f32_e32 v102, v120, v102
	v_add_f32_e32 v102, v121, v102
	s_waitcnt lgkmcnt(7)
	v_mfma_f32_32x32x16_bf16 v[70:85], v[244:247], v[134:137], v[70:85]
	ds_read_b128 v[244:247], v214 offset:57472
	v_add_f32_e32 v102, v116, v102
	v_add_f32_e32 v102, v117, v102
	v_add_f32_e32 v102, v114, v102
	v_add_f32_e32 v102, v115, v102
	s_waitcnt lgkmcnt(7)
	v_mfma_f32_32x32x16_bf16 v[86:101], v[180:183], v[138:141], v[86:101]
	v_add_f32_e32 v102, v128, v102
	v_add_f32_e32 v102, v129, v102
	v_add_f32_e32 v102, v122, v102
	v_add_f32_e32 v102, v123, v102
	s_waitcnt lgkmcnt(6)
	v_mfma_f32_32x32x16_bf16 v[70:85], v[184:187], v[138:141], v[70:85]
	v_add_f32_e32 v102, v118, v102
	v_add_f32_e32 v223, v119, v102
	v_mov_b32_e32 v224, v223
	s_nop 1
	v_permlane32_swap_b32_e32 v223, v224
	s_waitcnt lgkmcnt(5)
	v_mfma_f32_32x32x16_bf16 v[86:101], v[188:191], v[142:145], v[86:101]
	v_cvt_pk_bf16_f32 v102, v170, v171
	v_cvt_pk_bf16_f32 v103, v172, v173
	v_cvt_pk_bf16_f32 v104, v174, v176
	v_cvt_pk_bf16_f32 v105, v175, v177
	s_waitcnt lgkmcnt(4)
	v_mfma_f32_32x32x16_bf16 v[70:85], v[228:231], v[142:145], v[70:85]
	v_cvt_pk_bf16_f32 v66, v162, v163
	v_cvt_pk_bf16_f32 v67, v164, v166
	v_cvt_pk_bf16_f32 v68, v165, v167
	v_cvt_pk_bf16_f32 v69, v168, v169
	s_waitcnt lgkmcnt(3)
	v_mfma_f32_32x32x16_bf16 v[86:101], v[232:235], v[146:149], v[86:101]
	v_cvt_pk_bf16_f32 v106, v126, v127
	v_cvt_pk_bf16_f32 v107, v124, v125
	v_cvt_pk_bf16_f32 v108, v120, v121
	v_cvt_pk_bf16_f32 v109, v116, v117
	s_waitcnt lgkmcnt(2)
	v_mfma_f32_32x32x16_bf16 v[70:85], v[236:239], v[146:149], v[70:85]
	v_cvt_pk_bf16_f32 v110, v114, v115
	v_cvt_pk_bf16_f32 v111, v128, v129
	v_cvt_pk_bf16_f32 v112, v122, v123
	v_cvt_pk_bf16_f32 v113, v118, v119
	s_waitcnt lgkmcnt(1)
	v_mfma_f32_32x32x16_bf16 v[86:101], v[240:243], v[130:133], v[86:101]
	s_nop 1
	v_permlane32_swap_b32_e32 v102, v104
	v_permlane32_swap_b32_e32 v103, v105
	v_permlane32_swap_b32_e32 v66, v68
	v_permlane32_swap_b32_e32 v67, v69
	s_waitcnt lgkmcnt(0)
	v_mfma_f32_32x32x16_bf16 v[70:85], v[244:247], v[130:133], v[70:85]
	v_permlane32_swap_b32_e32 v106, v108
	v_permlane32_swap_b32_e32 v107, v109
	v_permlane32_swap_b32_e32 v110, v112
	v_permlane32_swap_b32_e32 v111, v113
	v_add_u32_e32 v114, 0x2000, v255
	global_load_dwordx4 v[162:165], v255, s[42:43]
	global_load_dwordx4 v[166:169], v114, s[42:43]
	v_readfirstlane_b32 s52, v1
	v_add_u32_e32 v115, 0x2000, v251
	s_nop 1
	s_lshl_b32 s52, s52, 4
	s_add_i32 m0, s52, 0x8000
	s_nop 0
	global_load_lds_dwordx4 v251, s[22:23]
	s_add_i32 m0, s52, 0xa000
	s_nop 0
	global_load_lds_dwordx4 v115, s[22:23]
	s_cmp_le_i32 s5, s13
	s_cselect_b64 s[52:53], -1, 0
	s_cmp_gt_i32 s4, s15
	s_cselect_b64 s[4:5], -1, 0
	s_and_b64 s[4:5], s[52:53], s[4:5]
	s_and_b64 vcc, exec, s[4:5]
	ds_read_b64_tr_b16 v[114:115], v202 offset:0x0
	ds_read_b64_tr_b16 v[116:117], v202 offset:0x800
	ds_read_b64_tr_b16 v[118:119], v202 offset:0x1000
	ds_read_b64_tr_b16 v[120:121], v202 offset:0x1800
	ds_read_b64_tr_b16 v[122:123], v202 offset:0x2000
	ds_read_b64_tr_b16 v[124:125], v202 offset:0x2800
	ds_read_b64_tr_b16 v[126:127], v202 offset:0x3000
	ds_read_b64_tr_b16 v[128:129], v202 offset:0x3800
	ds_read_b64_tr_b16 v[182:183], v202 offset:0x200
	ds_read_b64_tr_b16 v[184:185], v202 offset:0xa00
	ds_read_b64_tr_b16 v[186:187], v202 offset:0x1200
	ds_read_b64_tr_b16 v[188:189], v202 offset:0x1a00
	ds_read_b64_tr_b16 v[190:191], v202 offset:0x2200
	ds_read_b64_tr_b16 v[192:193], v202 offset:0x2a00
	s_cbranch_vccnz .Lh1_nomask
; __device__ __forceinline__ void mask_tile(f32x16& p0, f32x16& p1, int dq, unsigned W) {
;     const float NEG = -__builtin_inff();
; #pragma unroll
;     for (int r = 0; r < 16; ++r) {
;         const int c = (r & 3) + 8 * (r >> 2);
;         if ((unsigned)(dq - c) >= W) p0[r] = NEG;
;         if ((unsigned)(dq - c - 32) >= W) p1[r] = NEG;
;     }
; }
	v_add_u32_e32 v226, s80, v222
	v_subrev_u32_e32 v240, 64, v226
	v_cmp_gt_u32_e32 vcc, s85, v240
	v_add_u32_e32 v240, 0xffffffa0, v226
	s_nop 0
	v_cndmask_b32_e32 v86, v215, v86, vcc
	v_cmp_gt_u32_e32 vcc, s85, v240
	v_add_u32_e32 v240, 0xffffffbf, v226
	s_nop 0
	v_cndmask_b32_e32 v70, v215, v70, vcc
	v_cmp_gt_u32_e32 vcc, s85, v240
	v_add_u32_e32 v240, 0xffffff9f, v226
	s_nop 0
	v_cndmask_b32_e32 v87, v215, v87, vcc
	v_cmp_gt_u32_e32 vcc, s85, v240
	v_add_u32_e32 v240, 0xffffffbe, v226
	s_nop 0
	v_cndmask_b32_e32 v71, v215, v71, vcc
	v_cmp_gt_u32_e32 vcc, s85, v240
	v_add_u32_e32 v240, 0xffffff9e, v226
	s_nop 0
	v_cndmask_b32_e32 v88, v215, v88, vcc
	v_cmp_gt_u32_e32 vcc, s85, v240
	v_add_u32_e32 v240, 0xffffffbd, v226
	s_nop 0
	v_cndmask_b32_e32 v72, v215, v72, vcc
	v_cmp_gt_u32_e32 vcc, s85, v240
	v_add_u32_e32 v240, 0xffffff9d, v226
	s_nop 0
	v_cndmask_b32_e32 v89, v215, v89, vcc
	v_cmp_gt_u32_e32 vcc, s85, v240
	v_add_u32_e32 v240, 0xffffffb8, v226
	s_nop 0
	v_cndmask_b32_e32 v73, v215, v73, vcc
	v_cmp_gt_u32_e32 vcc, s85, v240
	v_add_u32_e32 v240, 0xffffff98, v226
	s_nop 0
	v_cndmask_b32_e32 v90, v215, v90, vcc
	v_cmp_gt_u32_e32 vcc, s85, v240
	v_add_u32_e32 v240, 0xffffffb7, v226
	s_nop 0
	v_cndmask_b32_e32 v74, v215, v74, vcc
	v_cmp_gt_u32_e32 vcc, s85, v240
	v_add_u32_e32 v240, 0xffffff97, v226
	s_nop 0
	v_cndmask_b32_e32 v91, v215, v91, vcc
	v_cmp_gt_u32_e32 vcc, s85, v240
	v_add_u32_e32 v240, 0xffffffb6, v226
	s_nop 0
	v_cndmask_b32_e32 v75, v215, v75, vcc
	v_cmp_gt_u32_e32 vcc, s85, v240
	v_add_u32_e32 v240, 0xffffff96, v226
	s_nop 0
	v_cndmask_b32_e32 v92, v215, v92, vcc
	v_cmp_gt_u32_e32 vcc, s85, v240
	v_add_u32_e32 v240, 0xffffffb5, v226
	s_nop 0
	v_cndmask_b32_e32 v76, v215, v76, vcc
	v_cmp_gt_u32_e32 vcc, s85, v240
	v_add_u32_e32 v240, 0xffffff95, v226
	s_nop 0
	v_cndmask_b32_e32 v93, v215, v93, vcc
	v_cmp_gt_u32_e32 vcc, s85, v240
	v_add_u32_e32 v240, 0xffffffb0, v226
	s_nop 0
	v_cndmask_b32_e32 v77, v215, v77, vcc
	v_cmp_gt_u32_e32 vcc, s85, v240
	v_add_u32_e32 v240, 0xffffff90, v226
	s_nop 0
	v_cndmask_b32_e32 v94, v215, v94, vcc
	v_cmp_gt_u32_e32 vcc, s85, v240
	v_add_u32_e32 v240, 0xffffffaf, v226
	s_nop 0
	v_cndmask_b32_e32 v78, v215, v78, vcc
	v_cmp_gt_u32_e32 vcc, s85, v240
	v_add_u32_e32 v240, 0xffffff8f, v226
	s_nop 0
	v_cndmask_b32_e32 v95, v215, v95, vcc
	v_cmp_gt_u32_e32 vcc, s85, v240
	v_add_u32_e32 v240, 0xffffffae, v226
	s_nop 0
	v_cndmask_b32_e32 v79, v215, v79, vcc
	v_cmp_gt_u32_e32 vcc, s85, v240
	v_add_u32_e32 v240, 0xffffff8e, v226
	s_nop 0
	v_cndmask_b32_e32 v96, v215, v96, vcc
	v_cmp_gt_u32_e32 vcc, s85, v240
	v_add_u32_e32 v240, 0xffffffad, v226
	s_nop 0
	v_cndmask_b32_e32 v80, v215, v80, vcc
	v_cmp_gt_u32_e32 vcc, s85, v240
	v_add_u32_e32 v240, 0xffffff8d, v226
	s_nop 0
	v_cndmask_b32_e32 v97, v215, v97, vcc
	v_cmp_gt_u32_e32 vcc, s85, v240
	v_add_u32_e32 v240, 0xffffffa8, v226
	s_nop 0
	v_cndmask_b32_e32 v81, v215, v81, vcc
	v_cmp_gt_u32_e32 vcc, s85, v240
	v_add_u32_e32 v240, 0xffffff88, v226
	s_nop 0
	v_cndmask_b32_e32 v98, v215, v98, vcc
	v_cmp_gt_u32_e32 vcc, s85, v240
	v_add_u32_e32 v240, 0xffffffa7, v226
	s_nop 0
	v_cndmask_b32_e32 v82, v215, v82, vcc
	v_cmp_gt_u32_e32 vcc, s85, v240
	v_add_u32_e32 v240, 0xffffff87, v226
	s_nop 0
	v_cndmask_b32_e32 v99, v215, v99, vcc
	v_cmp_gt_u32_e32 vcc, s85, v240
	v_add_u32_e32 v240, 0xffffffa6, v226
	s_nop 0
	v_cndmask_b32_e32 v83, v215, v83, vcc
	v_cmp_gt_u32_e32 vcc, s85, v240
	v_add_u32_e32 v240, 0xffffff86, v226
	s_nop 0
	v_cndmask_b32_e32 v100, v215, v100, vcc
	v_cmp_gt_u32_e32 vcc, s85, v240
	v_add_u32_e32 v240, 0xffffffa5, v226
	s_nop 0
	v_cndmask_b32_e32 v84, v215, v84, vcc
	v_cmp_gt_u32_e32 vcc, s85, v240
	v_add_u32_e32 v240, 0xffffff85, v226
	s_nop 0
	v_cndmask_b32_e32 v101, v215, v101, vcc
	v_cmp_gt_u32_e32 vcc, s85, v240
	s_nop 1
	v_cndmask_b32_e32 v85, v215, v85, vcc

; #define SBAR() __builtin_amdgcn_sched_barrier(0)
; #define VMW() asm volatile("s_waitcnt vmcnt(0)" ::: "memory")
; #define SLOAD_H(Kp, Vp, k0) do { S.st_v0 = load8<TIn>(ROW(Vp, k0, sr)); S.st_v1 = load8<TIn>(ROW(Vp, k0, 32 + sr));              \
;                          S.st_k0 = load8<TIn>(ROW(Kp, k0, sr)); S.st_k1 = load8<TIn>(ROW(Kp, k0, 32 + sr)); } while (0)
; #define SWRITE_HV(bf) do { *(bf16x8*)(V_lds + (bf) * SHM_V + vst0) = S.st_v0; *(bf16x8*)(V_lds + (bf) * SHM_V + vst1) = S.st_v1; } while (0)
; #define SWRITE_H(bf) do { SWRITE_HV(bf); SWRITE_HK(bf); } while (0)
; #define SLOAD_F(p, k0) do { S.sf0 = *(const f32x4*)ROW(p, k0, sr); S.sf1 = *(const f32x4*)(ROW(p, k0, sr) + 4);                \
;                             S.sf2 = *(const f32x4*)ROW(p, k0, 32 + sr); S.sf3 = *(const f32x4*)(ROW(p, k0, 32 + sr) + 4); } while (0)
; #define SWRITE_KF(bf) do { *(bf16x8*)(K_lds + (bf) * SHM_K + kws) = pack8(S.sf0, S.sf1); *(bf16x8*)(K_lds + (bf) * SHM_K + kws + 32 * 256) = pack8(S.sf2, S.sf3); } while (0)
; #define SWRITE_VF(bf) do { *(bf16x8*)(V_lds + (bf) * SHM_V + vst0) = pack8(S.sf0, S.sf1); *(bf16x8*)(V_lds + (bf) * SHM_V + vst1) = pack8(S.sf2, S.sf3); } while (0)
; template <int VB, bool SK>
; __device__ __forceinline__ void pv_tile(f32x16* o, int vb0, bf16x8 pa0, bf16x8 pa1, bf16x8 pa2, bf16x8 pa3, bool act) {
;     ...
;     PV_D0(0); PV_D0(1); PV_D0(2); PV_D0(3);
; template <class TIn, class TOut>
; __device__ __forceinline__ void causal_swa_block(const BlockRef<TIn, TOut>& cur, const BlockRef<TIn, TOut>& nxt, int skv, int W, char* lds, Seam<TIn>& S) {
;     ...
;     constexpr int NQL = F32 ? 16 : 8;
;     constexpr bool SK = WSKIP && !F32;
;     ...
;     f32x16 pA0, pA1, pB0, pB1; float mnA, mnB, alA, alB; bf16x8 pa0, pa1, pa2, pa3;
;     if constexpr (F32) { VMW(); SWRITE_VF(0); SBAR(); } else { SWRITE_HV(0); SBAR(); }
;     if (NT > 1) { if constexpr (F32) SLOAD_F((const float*)Kh, KBASE(1)); else SLOAD_H(Kh, Vh, KBASE(1)); }
;     SBAR(); qkt<0, SK>(pA0, pA1, K_lds, r32, hi, S.qr, ACT(0));
;     if constexpr (F32) { if (NT > 1) { VMW(); SWRITE_KF(1); SBAR(); SLOAD_F((const float*)Vh, KBASE(1)); } }
;     MASKT(pA0, pA1, 0); partialSM(pA0, pA1, m_reg, mnA, alA);
;     if (NT > 1) { VMW(); if constexpr (F32) { SWRITE_VF(1); SBAR(); if (NT > 2) SLOAD_F((const float*)Kh, KBASE(2)); } else SWRITE_H(1); }
;     __syncthreads();
.Lh1_back:
	v_fmamk_f32 v228, v86, 0x3e0293ee, v253
	v_fmamk_f32 v229, v87, 0x3e0293ee, v253
	s_waitcnt lgkmcnt(12)
	v_mfma_f32_32x32x16_bf16 v[50:65], v[66:69], v[186:189], v[50:65]
	ds_read_b64_tr_b16 v[182:183], v202 offset:0x600
	ds_read_b64_tr_b16 v[184:185], v202 offset:0xe00
	v_fmamk_f32 v230, v88, 0x3e0293ee, v253
	v_fmamk_f32 v231, v89, 0x3e0293ee, v253
	v_fmamk_f32 v232, v90, 0x3e0293ee, v253
	s_waitcnt lgkmcnt(12)
	v_mfma_f32_32x32x16_bf16 v[50:65], v[106:109], v[190:193], v[50:65]
	ds_read_b64_tr_b16 v[186:187], v202 offset:0x1600
	ds_read_b64_tr_b16 v[188:189], v202 offset:0x1e00
	v_fmamk_f32 v233, v91, 0x3e0293ee, v253
	v_fmamk_f32 v234, v92, 0x3e0293ee, v253
	v_fmamk_f32 v235, v93, 0x3e0293ee, v253
	s_waitcnt lgkmcnt(12)
	v_mfma_f32_32x32x16_bf16 v[50:65], v[110:113], v[244:247], v[50:65]
	ds_read_b64_tr_b16 v[190:191], v202 offset:0x2600
	ds_read_b64_tr_b16 v[192:193], v202 offset:0x2e00
	v_fmamk_f32 v236, v94, 0x3e0293ee, v253
	v_fmamk_f32 v237, v95, 0x3e0293ee, v253
	v_fmamk_f32 v238, v96, 0x3e0293ee, v253
	s_waitcnt lgkmcnt(12)
	v_mfma_f32_32x32x16_bf16 v[18:33], v[102:105], v[114:117], v[18:33]
	ds_read_b64_tr_b16 v[244:245], v202 offset:0x3600
	ds_read_b64_tr_b16 v[246:247], v202 offset:0x3e00
	v_fmamk_f32 v239, v97, 0x3e0293ee, v253
	v_fmamk_f32 v98, v98, 0x3e0293ee, v253
	v_fmamk_f32 v99, v99, 0x3e0293ee, v253
	s_waitcnt lgkmcnt(12)
	v_mfma_f32_32x32x16_bf16 v[18:33], v[66:69], v[118:121], v[18:33]
	v_fmamk_f32 v100, v100, 0x3e0293ee, v253
	v_fmamk_f32 v101, v101, 0x3e0293ee, v253
	v_fmamk_f32 v86, v70, 0x3e0293ee, v253
	s_waitcnt lgkmcnt(10)
	v_mfma_f32_32x32x16_bf16 v[18:33], v[106:109], v[122:125], v[18:33]
	v_fmamk_f32 v95, v71, 0x3e0293ee, v253
	v_fmamk_f32 v96, v72, 0x3e0293ee, v253
	v_fmamk_f32 v97, v73, 0x3e0293ee, v253
	s_waitcnt lgkmcnt(8)
	v_mfma_f32_32x32x16_bf16 v[18:33], v[110:113], v[126:129], v[18:33]
	v_fmamk_f32 v179, v74, 0x3e0293ee, v253
	v_fmamk_f32 v87, v75, 0x3e0293ee, v253
	v_fmamk_f32 v88, v76, 0x3e0293ee, v253
	s_waitcnt lgkmcnt(0)
	s_barrier
	s_waitcnt vmcnt(0)
	v_mfma_f32_32x32x16_bf16 v[2:17], v[102:105], v[182:185], v[2:17]
	ds_write_b128 v209, v[162:165]
	v_fmamk_f32 v89, v77, 0x3e0293ee, v253
	v_fmamk_f32 v90, v78, 0x3e0293ee, v253
	v_fmamk_f32 v91, v79, 0x3e0293ee, v253
	v_mfma_f32_32x32x16_bf16 v[2:17], v[66:69], v[186:189], v[2:17]
	ds_write_b128 v210, v[166:169]
	v_fmamk_f32 v92, v80, 0x3e0293ee, v253
	v_fmamk_f32 v93, v81, 0x3e0293ee, v253
	v_fmamk_f32 v94, v82, 0x3e0293ee, v253
	v_mfma_f32_32x32x16_bf16 v[2:17], v[106:109], v[190:193], v[2:17]
	v_fmamk_f32 v180, v83, 0x3e0293ee, v253
	v_fmamk_f32 v181, v84, 0x3e0293ee, v253
	v_fmamk_f32 v178, v85, 0x3e0293ee, v253
	v_mfma_f32_32x32x16_bf16 v[2:17], v[110:113], v[244:247], v[2:17]
	s_and_b64 vcc, exec, s[4:5]
	s_cbranch_vccnz .Lh1_noresc
	s_and_saveexec_b64 s[52:53], s[0:1]
	ds_write_b32 v219, v225 offset:128
	s_or_b64 exec, exec, s[52:53]
	s_waitcnt lgkmcnt(0)
	ds_read_b128 v[102:105], v218 offset:224
	ds_read_b128 v[106:109], v218 offset:192
	ds_read_b128 v[110:113], v218 offset:160
	ds_read_b128 v[114:117], v218 offset:128
	s_waitcnt lgkmcnt(3)
	v_pk_mul_f32 v[48:49], v[48:49], v[104:105]
	s_waitcnt lgkmcnt(2)
	v_pk_mul_f32 v[44:45], v[44:45], v[108:109]
	s_waitcnt lgkmcnt(1)
	v_pk_mul_f32 v[40:41], v[40:41], v[112:113]
	s_waitcnt lgkmcnt(0)
	v_pk_mul_f32 v[36:37], v[36:37], v[116:117]
	v_pk_mul_f32 v[46:47], v[46:47], v[102:103]
	v_pk_mul_f32 v[42:43], v[42:43], v[106:107]
	v_pk_mul_f32 v[38:39], v[38:39], v[110:111]
	v_pk_mul_f32 v[34:35], v[34:35], v[114:115]
	v_pk_mul_f32 v[64:65], v[64:65], v[104:105]
	v_pk_mul_f32 v[60:61], v[60:61], v[108:109]
	v_pk_mul_f32 v[56:57], v[56:57], v[112:113]
	v_pk_mul_f32 v[52:53], v[52:53], v[116:117]
	v_pk_mul_f32 v[62:63], v[62:63], v[102:103]
	v_pk_mul_f32 v[58:59], v[58:59], v[106:107]
	v_pk_mul_f32 v[54:55], v[54:55], v[110:111]
	v_pk_mul_f32 v[50:51], v[50:51], v[114:115]
	v_pk_mul_f32 v[32:33], v[32:33], v[104:105]
	v_pk_mul_f32 v[28:29], v[28:29], v[108:109]
	v_pk_mul_f32 v[24:25], v[24:25], v[112:113]
	v_pk_mul_f32 v[20:21], v[20:21], v[116:117]
	v_pk_mul_f32 v[30:31], v[30:31], v[102:103]
	v_pk_mul_f32 v[26:27], v[26:27], v[106:107]
	v_pk_mul_f32 v[22:23], v[22:23], v[110:111]
	v_pk_mul_f32 v[18:19], v[18:19], v[114:115]
	v_pk_mul_f32 v[16:17], v[16:17], v[104:105]
	v_pk_mul_f32 v[12:13], v[12:13], v[108:109]
	v_pk_mul_f32 v[8:9], v[8:9], v[112:113]
	v_pk_mul_f32 v[4:5], v[4:5], v[116:117]
	v_pk_mul_f32 v[14:15], v[14:15], v[102:103]
	v_pk_mul_f32 v[10:11], v[10:11], v[106:107]
	v_pk_mul_f32 v[6:7], v[6:7], v[110:111]
	v_pk_mul_f32 v[2:3], v[2:3], v[114:115]
; __device__ __forceinline__ void finishSM(f32x16& p0, f32x16& p1, float alpha, float& l_reg, bf16x8& pa0, bf16x8& pa1, bf16x8& pa2, bf16x8& pa3) {
;     for (int r = 0; r < 16; ++r) p1[r] = __builtin_amdgcn_exp2f(p1[r]);
;     float ps = 0; for (int r = 0; r < 16; ++r) ps += p0[r]; for (int r = 0; r < 16; ++r) ps += p1[r];
;     { auto rr = __builtin_amdgcn_permlane32_swap(__float_as_uint(ps), __float_as_uint(ps), false, false);
;       ps = __uint_as_float(rr[0]) + __uint_as_float(rr[1]); }
;     l_reg = l_reg * alpha + ps;
;     ...
;     PK4(p0, 0, pa0); PK4(p0, 8, pa1); PK4(p1, 0, pa2); PK4(p1, 8, pa3);
;     ...
; }
; template <int KB, bool SK>
; __device__ __forceinline__ void qkt(f32x16& p0, f32x16& p1, const char* K_lds, int r32, int hi, const bf16x8* qr, bool act) {
;     if (SK && !act) { const float NEG = -__builtin_inff();
; #pragma unroll
;         for (int r = 0; r < 16; ++r) { p0[r] = NEG; p1[r] = NEG; } return; }
;     p0 = f32x16{}; p1 = f32x16{};
;     const char* kb[4];
; #pragma unroll
;     for (int dd = 0; dd < 4; ++dd) kb[dd] = K_lds + KB * SHM_K + KSWZ(r32, (dd * 16 + hi * 8) * 2);
; #pragma unroll
;     for (int d0 = 0; d0 < 8; ++d0) { const char* a = kb[d0 & 3] + (d0 >> 2) * 128;
;         bf16x8 b0 = *reinterpret_cast<const bf16x8*>(a);
;         bf16x8 b1 = *reinterpret_cast<const bf16x8*>(a + 32 * 256);
;         const bf16x8 qf = qr[d0];
;         p0 = __builtin_amdgcn_mfma_f32_32x32x16_bf16(b0, qf, p0, 0, 0, 0);
;         p1 = __builtin_amdgcn_mfma_f32_32x32x16_bf16(b1, qf, p1, 0, 0, 0); }
; }
.Lh1_noresc:
	v_exp_f32_e32 v66, v228
	v_exp_f32_e32 v67, v229
	v_exp_f32_e32 v68, v230
	v_exp_f32_e32 v69, v231
	v_exp_f32_e32 v70, v232
	v_exp_f32_e32 v71, v233
	v_exp_f32_e32 v72, v234
	v_exp_f32_e32 v73, v235
	v_exp_f32_e32 v74, v236
	v_exp_f32_e32 v75, v237
	v_exp_f32_e32 v76, v238
	v_exp_f32_e32 v77, v239
	v_exp_f32_e32 v78, v98
	v_exp_f32_e32 v79, v99
	v_exp_f32_e32 v80, v100
	v_exp_f32_e32 v81, v101
	s_waitcnt lgkmcnt(0)
	s_barrier
	ds_read_b128 v[162:165], v211 offset:32768
	ds_read_b128 v[166:169], v211 offset:40960
	ds_read_b128 v[170:173], v212 offset:32768
	ds_read_b128 v[174:177], v212 offset:40960
	ds_read_b128 v[230:233], v213 offset:32768
	ds_read_b128 v[234:237], v213 offset:40960
	ds_read_b128 v[238:241], v214 offset:32768
	ds_read_b128 v[242:245], v214 offset:40960
	v_exp_f32_e32 v82, v86
	v_exp_f32_e32 v83, v95
	v_exp_f32_e32 v84, v96
	v_exp_f32_e32 v85, v97
	v_exp_f32_e32 v86, v179
	v_exp_f32_e32 v87, v87
	s_waitcnt lgkmcnt(7)
	v_mfma_f32_32x32x16_bf16 v[114:129], v[162:165], v[158:161], 0
	ds_read_b128 v[162:165], v211 offset:32896
	v_exp_f32_e32 v88, v88
	v_exp_f32_e32 v89, v89
	v_exp_f32_e32 v90, v90
	v_exp_f32_e32 v91, v91
	v_exp_f32_e32 v92, v92
	s_waitcnt lgkmcnt(7)
	v_mfma_f32_32x32x16_bf16 v[98:113], v[166:169], v[158:161], 0
	ds_read_b128 v[166:169], v211 offset:41088
	v_exp_f32_e32 v93, v93
	v_exp_f32_e32 v94, v94
	v_exp_f32_e32 v95, v180
	v_exp_f32_e32 v96, v181
	v_exp_f32_e32 v97, v178
	s_waitcnt lgkmcnt(7)
	v_mfma_f32_32x32x16_bf16 v[114:129], v[170:173], v[154:157], v[114:129]
	ds_read_b128 v[170:173], v212 offset:32896
	v_add_f32_e32 v178, 0, v66
	v_add_f32_e32 v178, v67, v178
	v_add_f32_e32 v178, v68, v178
	v_add_f32_e32 v178, v69, v178
	v_add_f32_e32 v178, v70, v178
	s_waitcnt lgkmcnt(7)
	v_mfma_f32_32x32x16_bf16 v[98:113], v[174:177], v[154:157], v[98:113]
	ds_read_b128 v[174:177], v212 offset:41088
	v_add_f32_e32 v178, v71, v178
	v_add_f32_e32 v178, v72, v178
	v_add_f32_e32 v178, v73, v178
	v_add_f32_e32 v178, v74, v178
	v_add_f32_e32 v178, v75, v178
	s_waitcnt lgkmcnt(7)
	v_mfma_f32_32x32x16_bf16 v[114:129], v[230:233], v[150:153], v[114:129]
	ds_read_b128 v[230:233], v213 offset:32896
	v_add_f32_e32 v178, v76, v178
	v_add_f32_e32 v178, v77, v178
	v_add_f32_e32 v178, v78, v178
	v_add_f32_e32 v178, v79, v178
	s_waitcnt lgkmcnt(7)
	v_mfma_f32_32x32x16_bf16 v[98:113], v[234:237], v[150:153], v[98:113]
	ds_read_b128 v[234:237], v213 offset:41088
	v_add_f32_e32 v178, v80, v178
	v_add_f32_e32 v178, v81, v178
	v_add_f32_e32 v178, v82, v178
	v_add_f32_e32 v178, v83, v178
	s_waitcnt lgkmcnt(7)
	v_mfma_f32_32x32x16_bf16 v[114:129], v[238:241], v[134:137], v[114:129]
	ds_read_b128 v[238:241], v214 offset:32896
	v_add_f32_e32 v178, v84, v178
	v_add_f32_e32 v178, v85, v178
	v_add_f32_e32 v178, v86, v178
	v_add_f32_e32 v178, v87, v178
	s_waitcnt lgkmcnt(7)
	v_mfma_f32_32x32x16_bf16 v[98:113], v[242:245], v[134:137], v[98:113]
	ds_read_b128 v[242:245], v214 offset:41088
	v_add_f32_e32 v178, v88, v178
	v_add_f32_e32 v178, v89, v178
	v_add_f32_e32 v178, v90, v178
	v_add_f32_e32 v178, v91, v178
	s_waitcnt lgkmcnt(7)
	v_mfma_f32_32x32x16_bf16 v[114:129], v[162:165], v[138:141], v[114:129]
	v_add_f32_e32 v178, v92, v178
	v_add_f32_e32 v178, v93, v178
	v_add_f32_e32 v178, v94, v178
	v_add_f32_e32 v178, v95, v178
	s_waitcnt lgkmcnt(6)
	v_mfma_f32_32x32x16_bf16 v[98:113], v[166:169], v[138:141], v[98:113]
	v_add_f32_e32 v178, v96, v178
	v_add_f32_e32 v228, v97, v178
	v_mov_b32_e32 v229, v228
	s_nop 1
	v_permlane32_swap_b32_e32 v228, v229
	s_waitcnt lgkmcnt(5)
	v_mfma_f32_32x32x16_bf16 v[114:129], v[170:173], v[142:145], v[114:129]
	v_cvt_pk_bf16_f32 v178, v66, v67
	v_cvt_pk_bf16_f32 v179, v68, v69
	v_cvt_pk_bf16_f32 v180, v70, v71
	v_cvt_pk_bf16_f32 v181, v72, v73
	s_waitcnt lgkmcnt(4)
	v_mfma_f32_32x32x16_bf16 v[98:113], v[174:177], v[142:145], v[98:113]
	v_cvt_pk_bf16_f32 v182, v74, v75
	v_cvt_pk_bf16_f32 v183, v76, v77
	v_cvt_pk_bf16_f32 v184, v78, v79
	v_cvt_pk_bf16_f32 v185, v80, v81
	s_waitcnt lgkmcnt(3)
	v_mfma_f32_32x32x16_bf16 v[114:129], v[230:233], v[146:149], v[114:129]
	v_cvt_pk_bf16_f32 v186, v82, v83
	v_cvt_pk_bf16_f32 v187, v84, v85
	v_cvt_pk_bf16_f32 v188, v86, v87
	v_cvt_pk_bf16_f32 v189, v88, v89
	s_waitcnt lgkmcnt(2)
	v_mfma_f32_32x32x16_bf16 v[98:113], v[234:237], v[146:149], v[98:113]
	v_cvt_pk_bf16_f32 v190, v90, v91
	v_cvt_pk_bf16_f32 v191, v92, v93
	v_cvt_pk_bf16_f32 v192, v94, v95
	v_cvt_pk_bf16_f32 v193, v96, v97
	s_waitcnt lgkmcnt(1)
	v_mfma_f32_32x32x16_bf16 v[114:129], v[238:241], v[130:133], v[114:129]
	s_nop 1
	v_permlane32_swap_b32_e32 v178, v180
	v_permlane32_swap_b32_e32 v179, v181
	v_permlane32_swap_b32_e32 v182, v184
	v_permlane32_swap_b32_e32 v183, v185
	s_waitcnt lgkmcnt(0)
	v_mfma_f32_32x32x16_bf16 v[98:113], v[242:245], v[130:133], v[98:113]
	v_permlane32_swap_b32_e32 v186, v188
	v_permlane32_swap_b32_e32 v187, v189
	v_permlane32_swap_b32_e32 v190, v192
	v_permlane32_swap_b32_e32 v191, v193
	s_add_i32 s4, s25, 1
	s_cmp_le_u32 s4, s24
	s_cselect_b64 s[76:77], -1, 0
	s_cmp_gt_u32 s4, s24
	s_cbranch_scc1 .LBB0_1137
	v_add_u32_e32 v84, 0x4000, v255
	v_add_u32_e32 v85, 0x6000, v255
	global_load_dwordx4 v[162:165], v84, s[42:43]
	global_load_dwordx4 v[166:169], v85, s[42:43]
	v_readfirstlane_b32 s52, v1
	v_add_u32_e32 v66, 0x4000, v251
	v_add_u32_e32 v67, 0x6000, v251
	s_nop 0
	s_lshl_b32 s52, s52, 4
	s_add_i32 m0, s52, 0xc000
	s_nop 0
	global_load_lds_dwordx4 v66, s[22:23]
	s_add_i32 m0, s52, 0xe000
	s_nop 0
	global_load_lds_dwordx4 v67, s[22:23]

; __device__ __forceinline__ void partialSM(f32x16& p0, f32x16& p1, float& m_reg, float& mn, float& alpha) {
;     float pmax = p0[0]; for (int r = 1; r < 16; ++r) pmax = fmaxf(pmax, p0[r]); for (int r = 0; r < 16; ++r) pmax = fmaxf(pmax, p1[r]);
;     { auto rr = __builtin_amdgcn_permlane32_swap(__float_as_uint(pmax), __float_as_uint(pmax), false, false);
;       pmax = fmaxf(__uint_as_float(rr[0]), __uint_as_float(rr[1])); }
;     constexpr float C2 = 1.4426950408889634f * SCALE;
;     if (__builtin_expect(__all((pmax - m_reg) * SCALE <= THR), 1)) { mn = m_reg; alpha = 1.f; }
;     else { mn = fmaxf(m_reg, pmax); alpha = __builtin_amdgcn_exp2f((m_reg - mn) * C2); m_reg = mn; }
;     const float mnL = -mn * C2;
;     for (int r = 0; r < 16; ++r) p0[r] = fmaf(p0[r], C2, mnL); for (int r = 0; r < 16; ++r) p1[r] = fmaf(p1[r], C2, mnL);
;     for (int r = 0; r < 16; ++r) p0[r] = __builtin_amdgcn_exp2f(p0[r]);
; }
; __device__ __forceinline__ void finishSM(f32x16& p0, f32x16& p1, float alpha, float& l_reg, bf16x8& pa0, bf16x8& pa1, bf16x8& pa2, bf16x8& pa3) {
;     for (int r = 0; r < 16; ++r) p1[r] = __builtin_amdgcn_exp2f(p1[r]);
;     float ps = 0; for (int r = 0; r < 16; ++r) ps += p0[r]; for (int r = 0; r < 16; ++r) ps += p1[r];
;     { auto rr = __builtin_amdgcn_permlane32_swap(__float_as_uint(ps), __float_as_uint(ps), false, false);
;       ps = __uint_as_float(rr[0]) + __uint_as_float(rr[1]); }
;     l_reg = l_reg * alpha + ps;
;     ...
;     PK4(p0, 0, pa0); PK4(p0, 8, pa1); PK4(p1, 0, pa2); PK4(p1, 8, pa3);
;     ...
; }
; template <int KB, bool SK>
; __device__ __forceinline__ void qkt(f32x16& p0, f32x16& p1, const char* K_lds, int r32, int hi, const bf16x8* qr, bool act) {
;     if (SK && !act) { const float NEG = -__builtin_inff();
; #pragma unroll
;         for (int r = 0; r < 16; ++r) { p0[r] = NEG; p1[r] = NEG; } return; }
;     p0 = f32x16{}; p1 = f32x16{};
;     const char* kb[4];
; #pragma unroll
;     for (int dd = 0; dd < 4; ++dd) kb[dd] = K_lds + KB * SHM_K + KSWZ(r32, (dd * 16 + hi * 8) * 2);
; #pragma unroll
;     for (int d0 = 0; d0 < 8; ++d0) { const char* a = kb[d0 & 3] + (d0 >> 2) * 128;
;         bf16x8 b0 = *reinterpret_cast<const bf16x8*>(a);
;         bf16x8 b1 = *reinterpret_cast<const bf16x8*>(a + 32 * 256);
;         const bf16x8 qf = qr[d0];
;         p0 = __builtin_amdgcn_mfma_f32_32x32x16_bf16(b0, qf, p0, 0, 0, 0);
.Lh2_back:
	v_fmamk_f32 v68, v114, 0x3e0293ee, v253
	v_fmamk_f32 v69, v115, 0x3e0293ee, v253
	s_waitcnt lgkmcnt(12)
	v_mfma_f32_32x32x16_bf16 v[50:65], v[182:185], v[90:93], v[50:65]
	ds_read_b64_tr_b16 v[86:87], v202 offset:0x4600
	ds_read_b64_tr_b16 v[88:89], v202 offset:0x4e00
	v_fmamk_f32 v70, v116, 0x3e0293ee, v253
	v_fmamk_f32 v71, v117, 0x3e0293ee, v253
	v_fmamk_f32 v79, v118, 0x3e0293ee, v253
	v_fmamk_f32 v80, v119, 0x3e0293ee, v253
	s_waitcnt lgkmcnt(12)
	v_mfma_f32_32x32x16_bf16 v[50:65], v[186:189], v[94:97], v[50:65]
	ds_read_b64_tr_b16 v[90:91], v202 offset:0x5600
	ds_read_b64_tr_b16 v[92:93], v202 offset:0x5e00
	v_fmamk_f32 v72, v120, 0x3e0293ee, v253
	v_fmamk_f32 v73, v121, 0x3e0293ee, v253
	v_fmamk_f32 v81, v122, 0x3e0293ee, v253
	v_fmamk_f32 v82, v123, 0x3e0293ee, v253
	s_waitcnt lgkmcnt(12)
	v_mfma_f32_32x32x16_bf16 v[50:65], v[190:193], v[246:249], v[50:65]
	ds_read_b64_tr_b16 v[94:95], v202 offset:0x6600
	ds_read_b64_tr_b16 v[96:97], v202 offset:0x6e00
	v_fmamk_f32 v74, v124, 0x3e0293ee, v253
	v_fmamk_f32 v75, v125, 0x3e0293ee, v253
	v_fmamk_f32 v76, v126, 0x3e0293ee, v253
	v_fmamk_f32 v77, v127, 0x3e0293ee, v253
	s_waitcnt lgkmcnt(12)
	v_mfma_f32_32x32x16_bf16 v[18:33], v[178:181], v[230:233], v[18:33]
	ds_read_b64_tr_b16 v[246:247], v202 offset:0x7600
	ds_read_b64_tr_b16 v[248:249], v202 offset:0x7e00
	v_fmamk_f32 v83, v128, 0x3e0293ee, v253
	v_fmamk_f32 v78, v129, 0x3e0293ee, v253
	v_fmamk_f32 v126, v98, 0x3e0293ee, v253
	v_fmamk_f32 v127, v99, 0x3e0293ee, v253
	s_waitcnt lgkmcnt(12)
	v_mfma_f32_32x32x16_bf16 v[18:33], v[182:185], v[234:237], v[18:33]
	v_fmamk_f32 v124, v100, 0x3e0293ee, v253
	v_fmamk_f32 v125, v101, 0x3e0293ee, v253
	v_fmamk_f32 v120, v102, 0x3e0293ee, v253
	s_waitcnt lgkmcnt(10)
	v_mfma_f32_32x32x16_bf16 v[18:33], v[186:189], v[238:241], v[18:33]
	v_fmamk_f32 v121, v103, 0x3e0293ee, v253
	v_fmamk_f32 v116, v104, 0x3e0293ee, v253
	v_fmamk_f32 v117, v105, 0x3e0293ee, v253
	s_waitcnt lgkmcnt(8)
	v_mfma_f32_32x32x16_bf16 v[18:33], v[190:193], v[242:245], v[18:33]
	v_fmamk_f32 v114, v106, 0x3e0293ee, v253
	v_fmamk_f32 v115, v107, 0x3e0293ee, v253
	v_fmamk_f32 v128, v108, 0x3e0293ee, v253
	s_waitcnt lgkmcnt(0)
	s_andn2_b64 vcc, exec, s[76:77]
	s_barrier
	s_cbranch_vccnz .Lh2_pvt_nowrite
	s_waitcnt vmcnt(0)
	v_mfma_f32_32x32x16_bf16 v[2:17], v[178:181], v[86:89], v[2:17]
	ds_write_b128 v209, v[162:165] offset:16384
	v_fmamk_f32 v129, v109, 0x3e0293ee, v253
	v_fmamk_f32 v122, v110, 0x3e0293ee, v253
	v_fmamk_f32 v123, v111, 0x3e0293ee, v253
	v_mfma_f32_32x32x16_bf16 v[2:17], v[182:185], v[90:93], v[2:17]
	ds_write_b128 v210, v[166:169] offset:16384
	v_fmamk_f32 v118, v112, 0x3e0293ee, v253
	v_fmamk_f32 v119, v113, 0x3e0293ee, v253
	v_add_f32_e32 v98, v223, v224
	v_mfma_f32_32x32x16_bf16 v[2:17], v[186:189], v[94:97], v[2:17]
	v_fmac_f32_e32 v98, v197, v221
	v_add_f32_e32 v221, v228, v229
	v_fmac_f32_e32 v221, v98, v225
	v_mfma_f32_32x32x16_bf16 v[2:17], v[190:193], v[246:249], v[2:17]
	s_branch .Lh2_pvt_join

; template <class TIn, class TOut>
; __device__ __forceinline__ void causal_swa_block(const BlockRef<TIn, TOut>& cur, const BlockRef<TIn, TOut>& nxt, int skv, int W, char* lds, Seam<TIn>& S) {
;     ...
;     for (int t = 1; t + 1 < NT; t += 2) {
;         HALF_STEP(pB0, pB1, mnB, alB, pA0, pA1, alA, t, 1, 0, 0);
;         HALF_STEP(pA0, pA1, mnA, alA, pB0, pB1, alB, t + 1, 0, 1, 1);
.Lh2_pvt_join:
.Lh2_nowrite:
	v_add_u32_e32 v194, 0x4000, v194
	v_add_u32_e32 v222, 0xffffff80, v222
	v_add_u32_e32 v255, 0x8000, v255
	v_add_u32_e32 v251, 0x8000, v251
	s_addk_i32 s26, 0x80
	s_add_i32 s25, s25, 2
	s_and_b64 vcc, exec, s[4:5]
	s_cbranch_vccnz .Lh2_noresc
	s_and_saveexec_b64 s[52:53], s[0:1]
	ds_write_b32 v219, v254 offset:128
	s_or_b64 exec, exec, s[52:53]
	s_waitcnt lgkmcnt(0)
	ds_read_b128 v[164:167], v218 offset:224
	ds_read_b128 v[168:171], v218 offset:192
	ds_read_b128 v[172:175], v218 offset:160
	ds_read_b128 v[180:183], v218 offset:128
	s_waitcnt lgkmcnt(3)
	v_pk_mul_f32 v[48:49], v[48:49], v[166:167]
	s_waitcnt lgkmcnt(2)
	v_pk_mul_f32 v[44:45], v[44:45], v[170:171]
	s_waitcnt lgkmcnt(1)
	v_pk_mul_f32 v[40:41], v[40:41], v[174:175]
	s_waitcnt lgkmcnt(0)
	v_pk_mul_f32 v[36:37], v[36:37], v[182:183]
	v_pk_mul_f32 v[46:47], v[46:47], v[164:165]
	v_pk_mul_f32 v[42:43], v[42:43], v[168:169]
	v_pk_mul_f32 v[38:39], v[38:39], v[172:173]
	v_pk_mul_f32 v[34:35], v[34:35], v[180:181]
	v_pk_mul_f32 v[64:65], v[64:65], v[166:167]
	v_pk_mul_f32 v[60:61], v[60:61], v[170:171]
	v_pk_mul_f32 v[56:57], v[56:57], v[174:175]
	v_pk_mul_f32 v[52:53], v[52:53], v[182:183]
	v_pk_mul_f32 v[62:63], v[62:63], v[164:165]
	v_pk_mul_f32 v[58:59], v[58:59], v[168:169]
	v_pk_mul_f32 v[54:55], v[54:55], v[172:173]
	v_pk_mul_f32 v[50:51], v[50:51], v[180:181]
	v_pk_mul_f32 v[32:33], v[32:33], v[166:167]
	v_pk_mul_f32 v[28:29], v[28:29], v[170:171]
	v_pk_mul_f32 v[24:25], v[24:25], v[174:175]
	v_pk_mul_f32 v[20:21], v[20:21], v[182:183]
	v_pk_mul_f32 v[30:31], v[30:31], v[164:165]
	v_pk_mul_f32 v[26:27], v[26:27], v[168:169]
	v_pk_mul_f32 v[22:23], v[22:23], v[172:173]
	v_pk_mul_f32 v[18:19], v[18:19], v[180:181]
	v_pk_mul_f32 v[16:17], v[16:17], v[166:167]
	v_pk_mul_f32 v[12:13], v[12:13], v[170:171]
	v_pk_mul_f32 v[8:9], v[8:9], v[174:175]
	v_pk_mul_f32 v[4:5], v[4:5], v[182:183]
	v_pk_mul_f32 v[14:15], v[14:15], v[164:165]
	v_pk_mul_f32 v[10:11], v[10:11], v[168:169]
	v_pk_mul_f32 v[6:7], v[6:7], v[172:173]
	v_pk_mul_f32 v[2:3], v[2:3], v[180:181]
